# scan compute: lane class = bit0^bit1 so the cross-lane d reduction uses quad_perm and mirror DPP modes only (no row_ror)
# baseline (speedup 1.0000x reference)
; __device__ __forceinline__ void phase_scan(CParams& p, LAS unsigned char* lds) {
;     ...
;         const bool prompt = item < 256; const int it = prompt ? item : item - 256; const int chain = it >> 1, hf = it & 1;
;         const int b = chain >> 4, h = chain & 15;
;         const int T = prompt ? 4096 : 16; const size_t m0 = prompt ? (size_t)b * 4096 : (size_t)MP + b * 16;
;         const int nch = (T + SCH - 1) / SCH;
;     ...
;             const int j = lane & 7, row = hf * 32 + wid * 8 + (lane >> 3);
;             f32x2 S[4];
; #pragma unroll
;             for (int i = 0; i < 4; ++i) S[i] = (f32x2){0.f, 0.f};
;             if (!prompt) { const float* sp = p.in[I_SWKV] + ((size_t)chain * 64 + row) * 64; const f32x4 a = *(const f32x4*)(sp + 4 * j), bq = *(const f32x4*)(sp + 32 + 4 * j);
;                 S[0] = a.lo; S[1] = a.hi; S[2] = bq.lo; S[3] = bq.hi; }
;             __syncthreads();
.LBB0_137:
	s_ashr_i32 s12, s1, 1
	s_and_b32 s33, s1, 1
	s_and_b64 s[2:3], s[50:51], exec
	s_cselect_b32 s1, 16, 0x1000
	s_add_i32 s2, s1, 31
	s_lshr_b32 s3, s2, 5
	s_mov_b64 s[54:55], -1
	s_and_b64 vcc, exec, s[4:5]
	s_cbranch_vccz .LBB0_147
	v_and_b32_e32 v112, 63, v192
	v_lshrrev_b32_e32 v113, 6, v192
	v_and_b32_e32 v114, 15, v112
	v_lshrrev_b32_e32 v115, 4, v112
	v_lshlrev_b32_e32 v116, 3, v113
	v_lshl_add_u32 v116, v115, 1, v116
	v_lshlrev_b32_e32 v100, 4, v114
	s_lshl_b32 s13, s33, 5
	v_add_u32_e32 v103, s13, v116
	v_lshlrev_b32_e32 v101, 2, v103
	v_add_u32_e32 v101, 0x500, v101
	v_lshlrev_b32_e32 v103, 8, v103
	v_add_u32_e32 v103, v103, v100
	v_lshrrev_b32_e32 v117, 1, v112
	v_xor_b32_e32 v117, v117, v112
	v_and_b32_e32 v117, 1, v117
	v_add_u32_e32 v102, v116, v117
	v_lshrrev_b32_e32 v114, 1, v114
	v_lshl_add_u32 v102, v102, 3, v114
	v_lshlrev_b32_e32 v102, 2, v102
	v_add_u32_e32 v102, 0x18600, v102
	v_cmp_eq_u32_e32 vcc, 1, v117
	v_lshlrev_b32_e32 v114, 7, v117
	v_lshrrev_b32_e32 v115, 1, v112
	v_mul_u32_u24_e32 v115, 0x600, v115
	v_lshl_add_u32 v115, v117, 4, v115
	v_lshl_add_u32 v115, v113, 5, v115
	s_lshl_b32 s13, s33, 7
	v_add_u32_e32 v115, s13, v115
	v_add_u32_e32 v118, 0x500, v115
	v_xor_b32_e32 v119, 0x80, v118
	s_mov_b32 s13, 0
	s_lshl_b64 s[54:55], s[12:13], 14
	s_cmp_eq_u64 s[50:51], 0
	s_cbranch_scc1 .Lsc_zero
	s_add_u32 s54, s18, s54
	s_addc_u32 s55, s19, s55
	s_nop 4
	global_load_dwordx4 v[104:107], v103, s[54:55]
	global_load_dwordx4 v[108:111], v103, s[54:55] offset:256
	s_waitcnt vmcnt(0)
	v_cndmask_b32_e32 v32, v104, v108, vcc
	v_cndmask_b32_e32 v33, v108, v104, vcc
	v_cndmask_b32_e32 v34, v105, v109, vcc
	v_cndmask_b32_e32 v35, v109, v105, vcc
	v_cndmask_b32_e32 v36, v106, v110, vcc
	v_cndmask_b32_e32 v37, v110, v106, vcc
	v_cndmask_b32_e32 v38, v107, v111, vcc
	v_cndmask_b32_e32 v39, v111, v107, vcc
	s_branch .Lsc_go

; #define LAS __attribute__((address_space(3)))
; __device__ __forceinline__ float reduce8(float x) { x += dppf<0xB1>(x); x += dppf<0x4E>(x); x += dppf<0x141>(x); return x; }
; __device__ __forceinline__ void phase_scan(CParams& p, LAS unsigned char* lds) {
;     ...
;                 for (int g16 = 0; g16 < nst; g16 += 16) {
;                     unsigned ywb = (unsigned)(YP_OFF + (g16 >> 4) * YP_BYTES + (wid * 64 + lane) * 4);
;                     asm volatile("" : "+v"(ywb));
;                     LAS float* yw = (LAS float*)(lds + ywb);
; #pragma unroll
;                     for (int s16 = 0; s16 < 16; ++s16) {
;                         scan_ld(nxt, base + (g16 + s16 + 1) * 384, vb + (g16 + s16 + 1) * 384);
;                         f32x2 d = S[0] * cur.n0.lo; d = S[1] * cur.n0.hi + d; d = S[2] * cur.n1.lo + d; d = S[3] * cur.n1.hi + d;
;                         const float sa = reduce8(d.x + d.y);
;                         const f32x2 sa2 = (f32x2){sa, sa}, v2 = (f32x2){cur.v, cur.v};
;                         S[0] = S[0] * cur.w0.lo + (cur.b0.lo * sa2 + cur.k0.lo * v2);
;                         S[1] = S[1] * cur.w0.hi + (cur.b0.hi * sa2 + cur.k0.hi * v2);
;                         S[2] = S[2] * cur.w1.lo + (cur.b1.lo * sa2 + cur.k1.lo * v2);
;                         S[3] = S[3] * cur.w1.hi + (cur.b1.hi * sa2 + cur.k1.hi * v2);
;                         f32x2 e = S[0] * cur.r0.lo; e = S[1] * cur.r0.hi + e; e = S[2] * cur.r1.lo + e; e = S[3] * cur.r1.hi + e;
;                         yw[s16 * 256] = e.x + e.y;
;                         cur = nxt;
;                     }
.Lsc_grp:
	ds_read_b128 v[64:67], v97 offset:2304
	s_waitcnt lgkmcnt(2)
	v_pk_mul_f32 v[84:85], v[32:33], v[40:41] op_sel_hi:[1,0]
	ds_read_b128 v[68:71], v97 offset:2560
	v_pk_fma_f32 v[84:85], v[34:35], v[40:41], v[84:85] op_sel:[0,1,0] op_sel_hi:[1,1,1]
	ds_read_b64 v[58:59], v98 offset:1536
	v_pk_fma_f32 v[84:85], v[36:37], v[42:43], v[84:85] op_sel_hi:[1,0,1]
	ds_read_b128 v[72:75], v97 offset:2048
	v_pk_fma_f32 v[84:85], v[38:39], v[42:43], v[84:85] op_sel:[0,1,0] op_sel_hi:[1,1,1]
	ds_read_b128 v[76:79], v97 offset:1792
	s_nop 0
	v_cndmask_b32_e32 v122, v56, v57, vcc
	v_cndmask_b32_e32 v123, v57, v56, vcc
	v_add_f32_dpp v84, v85, v84 quad_perm:[1,0,3,2] row_mask:0xf bank_mask:0xf bound_ctrl:1
	s_nop 0
	v_pk_mul_f32 v[86:87], v[122:123], v[48:49] op_sel_hi:[1,0]
	v_add_f32_dpp v84, v84, v84 quad_perm:[3,2,1,0] row_mask:0xf bank_mask:0xf bound_ctrl:1
	s_nop 0
	v_pk_mul_f32 v[88:89], v[122:123], v[48:49] op_sel:[0,1] op_sel_hi:[1,1]
	v_add_f32_dpp v84, v84, v84 row_half_mirror row_mask:0xf bank_mask:0xf bound_ctrl:1
	s_nop 0
	v_pk_mul_f32 v[90:91], v[122:123], v[50:51] op_sel_hi:[1,0]
	v_add_f32_dpp v84, v84, v84 row_mirror row_mask:0xf bank_mask:0xf bound_ctrl:1
	v_pk_mul_f32 v[92:93], v[122:123], v[50:51] op_sel:[0,1] op_sel_hi:[1,1]
	s_nop 0
	ds_read_b128 v[80:83], v97 offset:1536
	v_mov_b32_dpp v85, v84 quad_perm:[1,0,3,2] row_mask:0xf bank_mask:0xf
	s_nop 0
	v_pk_fma_f32 v[86:87], v[84:85], v[44:45], v[86:87] op_sel_hi:[1,0,1]
	v_pk_fma_f32 v[88:89], v[84:85], v[44:45], v[88:89] op_sel:[0,1,0] op_sel_hi:[1,1,1]
	v_pk_fma_f32 v[90:91], v[84:85], v[46:47], v[90:91] op_sel_hi:[1,0,1]
	v_pk_fma_f32 v[92:93], v[84:85], v[46:47], v[92:93] op_sel:[0,1,0] op_sel_hi:[1,1,1]
	v_pk_fma_f32 v[32:33], v[32:33], v[52:53], v[86:87] op_sel_hi:[1,0,1]
	v_pk_fma_f32 v[34:35], v[34:35], v[52:53], v[88:89] op_sel:[0,1,0] op_sel_hi:[1,1,1]
	v_pk_fma_f32 v[36:37], v[36:37], v[54:55], v[90:91] op_sel_hi:[1,0,1]
	v_pk_fma_f32 v[38:39], v[38:39], v[54:55], v[92:93] op_sel:[0,1,0] op_sel_hi:[1,1,1]
	ds_read_b128 v[40:43], v97 offset:3840
	s_waitcnt lgkmcnt(2)
	v_pk_mul_f32 v[84:85], v[32:33], v[64:65] op_sel_hi:[1,0]
	ds_read_b128 v[44:47], v97 offset:4096
	v_pk_fma_f32 v[84:85], v[34:35], v[64:65], v[84:85] op_sel:[0,1,0] op_sel_hi:[1,1,1]
	ds_read_b64 v[56:57], v98 offset:3072
	v_pk_fma_f32 v[84:85], v[36:37], v[66:67], v[84:85] op_sel_hi:[1,0,1]
	ds_read_b128 v[48:51], v97 offset:3584
	v_pk_fma_f32 v[84:85], v[38:39], v[66:67], v[84:85] op_sel:[0,1,0] op_sel_hi:[1,1,1]
	ds_read_b128 v[52:55], v97 offset:3328
	v_pk_mul_f32 v[94:95], v[32:33], v[60:61] op_sel_hi:[1,0]
	v_cndmask_b32_e32 v122, v58, v59, vcc
	v_cndmask_b32_e32 v123, v59, v58, vcc
	v_add_f32_dpp v84, v85, v84 quad_perm:[1,0,3,2] row_mask:0xf bank_mask:0xf bound_ctrl:1
	v_pk_fma_f32 v[94:95], v[34:35], v[60:61], v[94:95] op_sel:[0,1,0] op_sel_hi:[1,1,1]
	v_pk_mul_f32 v[86:87], v[122:123], v[72:73] op_sel_hi:[1,0]
	v_add_f32_dpp v84, v84, v84 quad_perm:[3,2,1,0] row_mask:0xf bank_mask:0xf bound_ctrl:1
	v_pk_fma_f32 v[94:95], v[36:37], v[62:63], v[94:95] op_sel_hi:[1,0,1]
	v_pk_mul_f32 v[88:89], v[122:123], v[72:73] op_sel:[0,1] op_sel_hi:[1,1]
	v_add_f32_dpp v84, v84, v84 row_half_mirror row_mask:0xf bank_mask:0xf bound_ctrl:1
	v_pk_fma_f32 v[94:95], v[38:39], v[62:63], v[94:95] op_sel:[0,1,0] op_sel_hi:[1,1,1]
	v_pk_mul_f32 v[90:91], v[122:123], v[74:75] op_sel_hi:[1,0]
	v_add_f32_dpp v84, v84, v84 row_mirror row_mask:0xf bank_mask:0xf bound_ctrl:1
	v_pk_mul_f32 v[92:93], v[122:123], v[74:75] op_sel:[0,1] op_sel_hi:[1,1]
	v_add_f32_dpp v96, v95, v94 quad_perm:[1,0,3,2] row_mask:0xf bank_mask:0xf bound_ctrl:1
	ds_read_b128 v[60:63], v97 offset:3072
	v_mov_b32_dpp v85, v84 quad_perm:[1,0,3,2] row_mask:0xf bank_mask:0xf
	ds_write_b32 v99, v96 offset:0
	v_pk_fma_f32 v[86:87], v[84:85], v[68:69], v[86:87] op_sel_hi:[1,0,1]
	v_pk_fma_f32 v[88:89], v[84:85], v[68:69], v[88:89] op_sel:[0,1,0] op_sel_hi:[1,1,1]
	v_pk_fma_f32 v[90:91], v[84:85], v[70:71], v[90:91] op_sel_hi:[1,0,1]
	v_pk_fma_f32 v[92:93], v[84:85], v[70:71], v[92:93] op_sel:[0,1,0] op_sel_hi:[1,1,1]
	v_pk_fma_f32 v[32:33], v[32:33], v[76:77], v[86:87] op_sel_hi:[1,0,1]
	v_pk_fma_f32 v[34:35], v[34:35], v[76:77], v[88:89] op_sel:[0,1,0] op_sel_hi:[1,1,1]
	v_pk_fma_f32 v[36:37], v[36:37], v[78:79], v[90:91] op_sel_hi:[1,0,1]
	v_pk_fma_f32 v[38:39], v[38:39], v[78:79], v[92:93] op_sel:[0,1,0] op_sel_hi:[1,1,1]
	ds_read_b128 v[64:67], v97 offset:5376
	s_waitcnt lgkmcnt(3)
; #define LAS __attribute__((address_space(3)))
; __device__ __forceinline__ float reduce8(float x) { x += dppf<0xB1>(x); x += dppf<0x4E>(x); x += dppf<0x141>(x); return x; }
; __device__ __forceinline__ void phase_scan(CParams& p, LAS unsigned char* lds) {
;     ...
;                 for (int g16 = 0; g16 < nst; g16 += 16) {
;                     unsigned ywb = (unsigned)(YP_OFF + (g16 >> 4) * YP_BYTES + (wid * 64 + lane) * 4);
;                     asm volatile("" : "+v"(ywb));
;                     LAS float* yw = (LAS float*)(lds + ywb);
; #pragma unroll
;                     for (int s16 = 0; s16 < 16; ++s16) {
;                         scan_ld(nxt, base + (g16 + s16 + 1) * 384, vb + (g16 + s16 + 1) * 384);
;                         f32x2 d = S[0] * cur.n0.lo; d = S[1] * cur.n0.hi + d; d = S[2] * cur.n1.lo + d; d = S[3] * cur.n1.hi + d;
;                         const float sa = reduce8(d.x + d.y);
;                         const f32x2 sa2 = (f32x2){sa, sa}, v2 = (f32x2){cur.v, cur.v};
;                         S[0] = S[0] * cur.w0.lo + (cur.b0.lo * sa2 + cur.k0.lo * v2);
;                         S[1] = S[1] * cur.w0.hi + (cur.b0.hi * sa2 + cur.k0.hi * v2);
;                         S[2] = S[2] * cur.w1.lo + (cur.b1.lo * sa2 + cur.k1.lo * v2);
;                         S[3] = S[3] * cur.w1.hi + (cur.b1.hi * sa2 + cur.k1.hi * v2);
;                         f32x2 e = S[0] * cur.r0.lo; e = S[1] * cur.r0.hi + e; e = S[2] * cur.r1.lo + e; e = S[3] * cur.r1.hi + e;
;                         yw[s16 * 256] = e.x + e.y;
;                         cur = nxt;
;                     }
	v_pk_mul_f32 v[84:85], v[32:33], v[40:41] op_sel_hi:[1,0]
	ds_read_b128 v[68:71], v97 offset:5632
	v_pk_fma_f32 v[84:85], v[34:35], v[40:41], v[84:85] op_sel:[0,1,0] op_sel_hi:[1,1,1]
	ds_read_b64 v[58:59], v98 offset:4608
	v_pk_fma_f32 v[84:85], v[36:37], v[42:43], v[84:85] op_sel_hi:[1,0,1]
	ds_read_b128 v[72:75], v97 offset:5120
	v_pk_fma_f32 v[84:85], v[38:39], v[42:43], v[84:85] op_sel:[0,1,0] op_sel_hi:[1,1,1]
	ds_read_b128 v[76:79], v97 offset:4864
	v_pk_mul_f32 v[94:95], v[32:33], v[80:81] op_sel_hi:[1,0]
	v_cndmask_b32_e32 v122, v56, v57, vcc
	v_cndmask_b32_e32 v123, v57, v56, vcc
	v_add_f32_dpp v84, v85, v84 quad_perm:[1,0,3,2] row_mask:0xf bank_mask:0xf bound_ctrl:1
	v_pk_fma_f32 v[94:95], v[34:35], v[80:81], v[94:95] op_sel:[0,1,0] op_sel_hi:[1,1,1]
	v_pk_mul_f32 v[86:87], v[122:123], v[48:49] op_sel_hi:[1,0]
	v_add_f32_dpp v84, v84, v84 quad_perm:[3,2,1,0] row_mask:0xf bank_mask:0xf bound_ctrl:1
	v_pk_fma_f32 v[94:95], v[36:37], v[82:83], v[94:95] op_sel_hi:[1,0,1]
	v_pk_mul_f32 v[88:89], v[122:123], v[48:49] op_sel:[0,1] op_sel_hi:[1,1]
	v_add_f32_dpp v84, v84, v84 row_half_mirror row_mask:0xf bank_mask:0xf bound_ctrl:1
	v_pk_fma_f32 v[94:95], v[38:39], v[82:83], v[94:95] op_sel:[0,1,0] op_sel_hi:[1,1,1]
	v_pk_mul_f32 v[90:91], v[122:123], v[50:51] op_sel_hi:[1,0]
	v_add_f32_dpp v84, v84, v84 row_mirror row_mask:0xf bank_mask:0xf bound_ctrl:1
	v_pk_mul_f32 v[92:93], v[122:123], v[50:51] op_sel:[0,1] op_sel_hi:[1,1]
	v_add_f32_dpp v96, v95, v94 quad_perm:[1,0,3,2] row_mask:0xf bank_mask:0xf bound_ctrl:1
	ds_read_b128 v[80:83], v97 offset:4608
	v_mov_b32_dpp v85, v84 quad_perm:[1,0,3,2] row_mask:0xf bank_mask:0xf
	ds_write_b32 v99, v96 offset:1024
	v_pk_fma_f32 v[86:87], v[84:85], v[44:45], v[86:87] op_sel_hi:[1,0,1]
	v_pk_fma_f32 v[88:89], v[84:85], v[44:45], v[88:89] op_sel:[0,1,0] op_sel_hi:[1,1,1]
	v_pk_fma_f32 v[90:91], v[84:85], v[46:47], v[90:91] op_sel_hi:[1,0,1]
	v_pk_fma_f32 v[92:93], v[84:85], v[46:47], v[92:93] op_sel:[0,1,0] op_sel_hi:[1,1,1]
	v_pk_fma_f32 v[32:33], v[32:33], v[52:53], v[86:87] op_sel_hi:[1,0,1]
	v_pk_fma_f32 v[34:35], v[34:35], v[52:53], v[88:89] op_sel:[0,1,0] op_sel_hi:[1,1,1]
	v_pk_fma_f32 v[36:37], v[36:37], v[54:55], v[90:91] op_sel_hi:[1,0,1]
	v_pk_fma_f32 v[38:39], v[38:39], v[54:55], v[92:93] op_sel:[0,1,0] op_sel_hi:[1,1,1]
	ds_read_b128 v[40:43], v97 offset:6912
	s_waitcnt lgkmcnt(3)
	v_pk_mul_f32 v[84:85], v[32:33], v[64:65] op_sel_hi:[1,0]
	ds_read_b128 v[44:47], v97 offset:7168
	v_pk_fma_f32 v[84:85], v[34:35], v[64:65], v[84:85] op_sel:[0,1,0] op_sel_hi:[1,1,1]
	ds_read_b64 v[56:57], v98 offset:6144
	v_pk_fma_f32 v[84:85], v[36:37], v[66:67], v[84:85] op_sel_hi:[1,0,1]
	ds_read_b128 v[48:51], v97 offset:6656
	v_pk_fma_f32 v[84:85], v[38:39], v[66:67], v[84:85] op_sel:[0,1,0] op_sel_hi:[1,1,1]
	ds_read_b128 v[52:55], v97 offset:6400
	v_pk_mul_f32 v[94:95], v[32:33], v[60:61] op_sel_hi:[1,0]
	v_cndmask_b32_e32 v122, v58, v59, vcc
	v_cndmask_b32_e32 v123, v59, v58, vcc
	v_add_f32_dpp v84, v85, v84 quad_perm:[1,0,3,2] row_mask:0xf bank_mask:0xf bound_ctrl:1
	v_pk_fma_f32 v[94:95], v[34:35], v[60:61], v[94:95] op_sel:[0,1,0] op_sel_hi:[1,1,1]
	v_pk_mul_f32 v[86:87], v[122:123], v[72:73] op_sel_hi:[1,0]
	v_add_f32_dpp v84, v84, v84 quad_perm:[3,2,1,0] row_mask:0xf bank_mask:0xf bound_ctrl:1
	v_pk_fma_f32 v[94:95], v[36:37], v[62:63], v[94:95] op_sel_hi:[1,0,1]
	v_pk_mul_f32 v[88:89], v[122:123], v[72:73] op_sel:[0,1] op_sel_hi:[1,1]
	v_add_f32_dpp v84, v84, v84 row_half_mirror row_mask:0xf bank_mask:0xf bound_ctrl:1
	v_pk_fma_f32 v[94:95], v[38:39], v[62:63], v[94:95] op_sel:[0,1,0] op_sel_hi:[1,1,1]
	v_pk_mul_f32 v[90:91], v[122:123], v[74:75] op_sel_hi:[1,0]
	v_add_f32_dpp v84, v84, v84 row_mirror row_mask:0xf bank_mask:0xf bound_ctrl:1
	v_pk_mul_f32 v[92:93], v[122:123], v[74:75] op_sel:[0,1] op_sel_hi:[1,1]
	v_add_f32_dpp v96, v95, v94 quad_perm:[1,0,3,2] row_mask:0xf bank_mask:0xf bound_ctrl:1
	ds_read_b128 v[60:63], v97 offset:6144
	v_mov_b32_dpp v85, v84 quad_perm:[1,0,3,2] row_mask:0xf bank_mask:0xf
	ds_write_b32 v99, v96 offset:2048
	v_pk_fma_f32 v[86:87], v[84:85], v[68:69], v[86:87] op_sel_hi:[1,0,1]
	v_pk_fma_f32 v[88:89], v[84:85], v[68:69], v[88:89] op_sel:[0,1,0] op_sel_hi:[1,1,1]
	v_pk_fma_f32 v[90:91], v[84:85], v[70:71], v[90:91] op_sel_hi:[1,0,1]
	v_pk_fma_f32 v[92:93], v[84:85], v[70:71], v[92:93] op_sel:[0,1,0] op_sel_hi:[1,1,1]
	v_pk_fma_f32 v[32:33], v[32:33], v[76:77], v[86:87] op_sel_hi:[1,0,1]
	v_pk_fma_f32 v[34:35], v[34:35], v[76:77], v[88:89] op_sel:[0,1,0] op_sel_hi:[1,1,1]
	v_pk_fma_f32 v[36:37], v[36:37], v[78:79], v[90:91] op_sel_hi:[1,0,1]
	v_pk_fma_f32 v[38:39], v[38:39], v[78:79], v[92:93] op_sel:[0,1,0] op_sel_hi:[1,1,1]
	ds_read_b128 v[64:67], v97 offset:8448
	s_waitcnt lgkmcnt(3)
; #define LAS __attribute__((address_space(3)))
; __device__ __forceinline__ float reduce8(float x) { x += dppf<0xB1>(x); x += dppf<0x4E>(x); x += dppf<0x141>(x); return x; }
; __device__ __forceinline__ void phase_scan(CParams& p, LAS unsigned char* lds) {
;     ...
;                 for (int g16 = 0; g16 < nst; g16 += 16) {
;                     unsigned ywb = (unsigned)(YP_OFF + (g16 >> 4) * YP_BYTES + (wid * 64 + lane) * 4);
;                     asm volatile("" : "+v"(ywb));
;                     LAS float* yw = (LAS float*)(lds + ywb);
; #pragma unroll
;                     for (int s16 = 0; s16 < 16; ++s16) {
;                         scan_ld(nxt, base + (g16 + s16 + 1) * 384, vb + (g16 + s16 + 1) * 384);
;                         f32x2 d = S[0] * cur.n0.lo; d = S[1] * cur.n0.hi + d; d = S[2] * cur.n1.lo + d; d = S[3] * cur.n1.hi + d;
;                         const float sa = reduce8(d.x + d.y);
;                         const f32x2 sa2 = (f32x2){sa, sa}, v2 = (f32x2){cur.v, cur.v};
;                         S[0] = S[0] * cur.w0.lo + (cur.b0.lo * sa2 + cur.k0.lo * v2);
;                         S[1] = S[1] * cur.w0.hi + (cur.b0.hi * sa2 + cur.k0.hi * v2);
;                         S[2] = S[2] * cur.w1.lo + (cur.b1.lo * sa2 + cur.k1.lo * v2);
;                         S[3] = S[3] * cur.w1.hi + (cur.b1.hi * sa2 + cur.k1.hi * v2);
;                         f32x2 e = S[0] * cur.r0.lo; e = S[1] * cur.r0.hi + e; e = S[2] * cur.r1.lo + e; e = S[3] * cur.r1.hi + e;
;                         yw[s16 * 256] = e.x + e.y;
;                         cur = nxt;
;                     }
	v_pk_mul_f32 v[84:85], v[32:33], v[40:41] op_sel_hi:[1,0]
	ds_read_b128 v[68:71], v97 offset:8704
	v_pk_fma_f32 v[84:85], v[34:35], v[40:41], v[84:85] op_sel:[0,1,0] op_sel_hi:[1,1,1]
	ds_read_b64 v[58:59], v98 offset:7680
	v_pk_fma_f32 v[84:85], v[36:37], v[42:43], v[84:85] op_sel_hi:[1,0,1]
	ds_read_b128 v[72:75], v97 offset:8192
	v_pk_fma_f32 v[84:85], v[38:39], v[42:43], v[84:85] op_sel:[0,1,0] op_sel_hi:[1,1,1]
	ds_read_b128 v[76:79], v97 offset:7936
	v_pk_mul_f32 v[94:95], v[32:33], v[80:81] op_sel_hi:[1,0]
	v_cndmask_b32_e32 v122, v56, v57, vcc
	v_cndmask_b32_e32 v123, v57, v56, vcc
	v_add_f32_dpp v84, v85, v84 quad_perm:[1,0,3,2] row_mask:0xf bank_mask:0xf bound_ctrl:1
	v_pk_fma_f32 v[94:95], v[34:35], v[80:81], v[94:95] op_sel:[0,1,0] op_sel_hi:[1,1,1]
	v_pk_mul_f32 v[86:87], v[122:123], v[48:49] op_sel_hi:[1,0]
	v_add_f32_dpp v84, v84, v84 quad_perm:[3,2,1,0] row_mask:0xf bank_mask:0xf bound_ctrl:1
	v_pk_fma_f32 v[94:95], v[36:37], v[82:83], v[94:95] op_sel_hi:[1,0,1]
	v_pk_mul_f32 v[88:89], v[122:123], v[48:49] op_sel:[0,1] op_sel_hi:[1,1]
	v_add_f32_dpp v84, v84, v84 row_half_mirror row_mask:0xf bank_mask:0xf bound_ctrl:1
	v_pk_fma_f32 v[94:95], v[38:39], v[82:83], v[94:95] op_sel:[0,1,0] op_sel_hi:[1,1,1]
	v_pk_mul_f32 v[90:91], v[122:123], v[50:51] op_sel_hi:[1,0]
	v_add_f32_dpp v84, v84, v84 row_mirror row_mask:0xf bank_mask:0xf bound_ctrl:1
	v_pk_mul_f32 v[92:93], v[122:123], v[50:51] op_sel:[0,1] op_sel_hi:[1,1]
	v_add_f32_dpp v96, v95, v94 quad_perm:[1,0,3,2] row_mask:0xf bank_mask:0xf bound_ctrl:1
	ds_read_b128 v[80:83], v97 offset:7680
	v_mov_b32_dpp v85, v84 quad_perm:[1,0,3,2] row_mask:0xf bank_mask:0xf
	ds_write_b32 v99, v96 offset:3072
	v_pk_fma_f32 v[86:87], v[84:85], v[44:45], v[86:87] op_sel_hi:[1,0,1]
	v_pk_fma_f32 v[88:89], v[84:85], v[44:45], v[88:89] op_sel:[0,1,0] op_sel_hi:[1,1,1]
	v_pk_fma_f32 v[90:91], v[84:85], v[46:47], v[90:91] op_sel_hi:[1,0,1]
	v_pk_fma_f32 v[92:93], v[84:85], v[46:47], v[92:93] op_sel:[0,1,0] op_sel_hi:[1,1,1]
	v_pk_fma_f32 v[32:33], v[32:33], v[52:53], v[86:87] op_sel_hi:[1,0,1]
	v_pk_fma_f32 v[34:35], v[34:35], v[52:53], v[88:89] op_sel:[0,1,0] op_sel_hi:[1,1,1]
	v_pk_fma_f32 v[36:37], v[36:37], v[54:55], v[90:91] op_sel_hi:[1,0,1]
	v_pk_fma_f32 v[38:39], v[38:39], v[54:55], v[92:93] op_sel:[0,1,0] op_sel_hi:[1,1,1]
	ds_read_b128 v[40:43], v97 offset:9984
	s_waitcnt lgkmcnt(3)
	v_pk_mul_f32 v[84:85], v[32:33], v[64:65] op_sel_hi:[1,0]
	ds_read_b128 v[44:47], v97 offset:10240
	v_pk_fma_f32 v[84:85], v[34:35], v[64:65], v[84:85] op_sel:[0,1,0] op_sel_hi:[1,1,1]
	ds_read_b64 v[56:57], v98 offset:9216
	v_pk_fma_f32 v[84:85], v[36:37], v[66:67], v[84:85] op_sel_hi:[1,0,1]
	ds_read_b128 v[48:51], v97 offset:9728
	v_pk_fma_f32 v[84:85], v[38:39], v[66:67], v[84:85] op_sel:[0,1,0] op_sel_hi:[1,1,1]
	ds_read_b128 v[52:55], v97 offset:9472
	v_pk_mul_f32 v[94:95], v[32:33], v[60:61] op_sel_hi:[1,0]
	v_cndmask_b32_e32 v122, v58, v59, vcc
	v_cndmask_b32_e32 v123, v59, v58, vcc
	v_add_f32_dpp v84, v85, v84 quad_perm:[1,0,3,2] row_mask:0xf bank_mask:0xf bound_ctrl:1
	v_pk_fma_f32 v[94:95], v[34:35], v[60:61], v[94:95] op_sel:[0,1,0] op_sel_hi:[1,1,1]
	v_pk_mul_f32 v[86:87], v[122:123], v[72:73] op_sel_hi:[1,0]
	v_add_f32_dpp v84, v84, v84 quad_perm:[3,2,1,0] row_mask:0xf bank_mask:0xf bound_ctrl:1
	v_pk_fma_f32 v[94:95], v[36:37], v[62:63], v[94:95] op_sel_hi:[1,0,1]
	v_pk_mul_f32 v[88:89], v[122:123], v[72:73] op_sel:[0,1] op_sel_hi:[1,1]
	v_add_f32_dpp v84, v84, v84 row_half_mirror row_mask:0xf bank_mask:0xf bound_ctrl:1
	v_pk_fma_f32 v[94:95], v[38:39], v[62:63], v[94:95] op_sel:[0,1,0] op_sel_hi:[1,1,1]
	v_pk_mul_f32 v[90:91], v[122:123], v[74:75] op_sel_hi:[1,0]
	v_add_f32_dpp v84, v84, v84 row_mirror row_mask:0xf bank_mask:0xf bound_ctrl:1
	v_pk_mul_f32 v[92:93], v[122:123], v[74:75] op_sel:[0,1] op_sel_hi:[1,1]
	v_add_f32_dpp v96, v95, v94 quad_perm:[1,0,3,2] row_mask:0xf bank_mask:0xf bound_ctrl:1
	ds_read_b128 v[60:63], v97 offset:9216
	v_mov_b32_dpp v85, v84 quad_perm:[1,0,3,2] row_mask:0xf bank_mask:0xf
	ds_write_b32 v99, v96 offset:4096
	v_pk_fma_f32 v[86:87], v[84:85], v[68:69], v[86:87] op_sel_hi:[1,0,1]
	v_pk_fma_f32 v[88:89], v[84:85], v[68:69], v[88:89] op_sel:[0,1,0] op_sel_hi:[1,1,1]
	v_pk_fma_f32 v[90:91], v[84:85], v[70:71], v[90:91] op_sel_hi:[1,0,1]
	v_pk_fma_f32 v[92:93], v[84:85], v[70:71], v[92:93] op_sel:[0,1,0] op_sel_hi:[1,1,1]
	v_pk_fma_f32 v[32:33], v[32:33], v[76:77], v[86:87] op_sel_hi:[1,0,1]
	v_pk_fma_f32 v[34:35], v[34:35], v[76:77], v[88:89] op_sel:[0,1,0] op_sel_hi:[1,1,1]
	v_pk_fma_f32 v[36:37], v[36:37], v[78:79], v[90:91] op_sel_hi:[1,0,1]
	v_pk_fma_f32 v[38:39], v[38:39], v[78:79], v[92:93] op_sel:[0,1,0] op_sel_hi:[1,1,1]
	ds_read_b128 v[64:67], v97 offset:11520
	s_waitcnt lgkmcnt(3)
; #define LAS __attribute__((address_space(3)))
; __device__ __forceinline__ float reduce8(float x) { x += dppf<0xB1>(x); x += dppf<0x4E>(x); x += dppf<0x141>(x); return x; }
; __device__ __forceinline__ void phase_scan(CParams& p, LAS unsigned char* lds) {
;     ...
;                 for (int g16 = 0; g16 < nst; g16 += 16) {
;                     unsigned ywb = (unsigned)(YP_OFF + (g16 >> 4) * YP_BYTES + (wid * 64 + lane) * 4);
;                     asm volatile("" : "+v"(ywb));
;                     LAS float* yw = (LAS float*)(lds + ywb);
; #pragma unroll
;                     for (int s16 = 0; s16 < 16; ++s16) {
;                         scan_ld(nxt, base + (g16 + s16 + 1) * 384, vb + (g16 + s16 + 1) * 384);
;                         f32x2 d = S[0] * cur.n0.lo; d = S[1] * cur.n0.hi + d; d = S[2] * cur.n1.lo + d; d = S[3] * cur.n1.hi + d;
;                         const float sa = reduce8(d.x + d.y);
;                         const f32x2 sa2 = (f32x2){sa, sa}, v2 = (f32x2){cur.v, cur.v};
;                         S[0] = S[0] * cur.w0.lo + (cur.b0.lo * sa2 + cur.k0.lo * v2);
;                         S[1] = S[1] * cur.w0.hi + (cur.b0.hi * sa2 + cur.k0.hi * v2);
;                         S[2] = S[2] * cur.w1.lo + (cur.b1.lo * sa2 + cur.k1.lo * v2);
;                         S[3] = S[3] * cur.w1.hi + (cur.b1.hi * sa2 + cur.k1.hi * v2);
;                         f32x2 e = S[0] * cur.r0.lo; e = S[1] * cur.r0.hi + e; e = S[2] * cur.r1.lo + e; e = S[3] * cur.r1.hi + e;
;                         yw[s16 * 256] = e.x + e.y;
;                         cur = nxt;
;                     }
	v_pk_mul_f32 v[84:85], v[32:33], v[40:41] op_sel_hi:[1,0]
	ds_read_b128 v[68:71], v97 offset:11776
	v_pk_fma_f32 v[84:85], v[34:35], v[40:41], v[84:85] op_sel:[0,1,0] op_sel_hi:[1,1,1]
	ds_read_b64 v[58:59], v98 offset:10752
	v_pk_fma_f32 v[84:85], v[36:37], v[42:43], v[84:85] op_sel_hi:[1,0,1]
	ds_read_b128 v[72:75], v97 offset:11264
	v_pk_fma_f32 v[84:85], v[38:39], v[42:43], v[84:85] op_sel:[0,1,0] op_sel_hi:[1,1,1]
	ds_read_b128 v[76:79], v97 offset:11008
	v_pk_mul_f32 v[94:95], v[32:33], v[80:81] op_sel_hi:[1,0]
	v_cndmask_b32_e32 v122, v56, v57, vcc
	v_cndmask_b32_e32 v123, v57, v56, vcc
	v_add_f32_dpp v84, v85, v84 quad_perm:[1,0,3,2] row_mask:0xf bank_mask:0xf bound_ctrl:1
	v_pk_fma_f32 v[94:95], v[34:35], v[80:81], v[94:95] op_sel:[0,1,0] op_sel_hi:[1,1,1]
	v_pk_mul_f32 v[86:87], v[122:123], v[48:49] op_sel_hi:[1,0]
	v_add_f32_dpp v84, v84, v84 quad_perm:[3,2,1,0] row_mask:0xf bank_mask:0xf bound_ctrl:1
	v_pk_fma_f32 v[94:95], v[36:37], v[82:83], v[94:95] op_sel_hi:[1,0,1]
	v_pk_mul_f32 v[88:89], v[122:123], v[48:49] op_sel:[0,1] op_sel_hi:[1,1]
	v_add_f32_dpp v84, v84, v84 row_half_mirror row_mask:0xf bank_mask:0xf bound_ctrl:1
	v_pk_fma_f32 v[94:95], v[38:39], v[82:83], v[94:95] op_sel:[0,1,0] op_sel_hi:[1,1,1]
	v_pk_mul_f32 v[90:91], v[122:123], v[50:51] op_sel_hi:[1,0]
	v_add_f32_dpp v84, v84, v84 row_mirror row_mask:0xf bank_mask:0xf bound_ctrl:1
	v_pk_mul_f32 v[92:93], v[122:123], v[50:51] op_sel:[0,1] op_sel_hi:[1,1]
	v_add_f32_dpp v96, v95, v94 quad_perm:[1,0,3,2] row_mask:0xf bank_mask:0xf bound_ctrl:1
	ds_read_b128 v[80:83], v97 offset:10752
	v_mov_b32_dpp v85, v84 quad_perm:[1,0,3,2] row_mask:0xf bank_mask:0xf
	ds_write_b32 v99, v96 offset:5120
	v_pk_fma_f32 v[86:87], v[84:85], v[44:45], v[86:87] op_sel_hi:[1,0,1]
	v_pk_fma_f32 v[88:89], v[84:85], v[44:45], v[88:89] op_sel:[0,1,0] op_sel_hi:[1,1,1]
	v_pk_fma_f32 v[90:91], v[84:85], v[46:47], v[90:91] op_sel_hi:[1,0,1]
	v_pk_fma_f32 v[92:93], v[84:85], v[46:47], v[92:93] op_sel:[0,1,0] op_sel_hi:[1,1,1]
	v_pk_fma_f32 v[32:33], v[32:33], v[52:53], v[86:87] op_sel_hi:[1,0,1]
	v_pk_fma_f32 v[34:35], v[34:35], v[52:53], v[88:89] op_sel:[0,1,0] op_sel_hi:[1,1,1]
	v_pk_fma_f32 v[36:37], v[36:37], v[54:55], v[90:91] op_sel_hi:[1,0,1]
	v_pk_fma_f32 v[38:39], v[38:39], v[54:55], v[92:93] op_sel:[0,1,0] op_sel_hi:[1,1,1]
	ds_read_b128 v[40:43], v97 offset:13056
	s_waitcnt lgkmcnt(3)
	v_pk_mul_f32 v[84:85], v[32:33], v[64:65] op_sel_hi:[1,0]
	ds_read_b128 v[44:47], v97 offset:13312
	v_pk_fma_f32 v[84:85], v[34:35], v[64:65], v[84:85] op_sel:[0,1,0] op_sel_hi:[1,1,1]
	ds_read_b64 v[56:57], v98 offset:12288
	v_pk_fma_f32 v[84:85], v[36:37], v[66:67], v[84:85] op_sel_hi:[1,0,1]
	ds_read_b128 v[48:51], v97 offset:12800
	v_pk_fma_f32 v[84:85], v[38:39], v[66:67], v[84:85] op_sel:[0,1,0] op_sel_hi:[1,1,1]
	ds_read_b128 v[52:55], v97 offset:12544
	v_pk_mul_f32 v[94:95], v[32:33], v[60:61] op_sel_hi:[1,0]
	v_cndmask_b32_e32 v122, v58, v59, vcc
	v_cndmask_b32_e32 v123, v59, v58, vcc
	v_add_f32_dpp v84, v85, v84 quad_perm:[1,0,3,2] row_mask:0xf bank_mask:0xf bound_ctrl:1
	v_pk_fma_f32 v[94:95], v[34:35], v[60:61], v[94:95] op_sel:[0,1,0] op_sel_hi:[1,1,1]
	v_pk_mul_f32 v[86:87], v[122:123], v[72:73] op_sel_hi:[1,0]
	v_add_f32_dpp v84, v84, v84 quad_perm:[3,2,1,0] row_mask:0xf bank_mask:0xf bound_ctrl:1
	v_pk_fma_f32 v[94:95], v[36:37], v[62:63], v[94:95] op_sel_hi:[1,0,1]
	v_pk_mul_f32 v[88:89], v[122:123], v[72:73] op_sel:[0,1] op_sel_hi:[1,1]
	v_add_f32_dpp v84, v84, v84 row_half_mirror row_mask:0xf bank_mask:0xf bound_ctrl:1
	v_pk_fma_f32 v[94:95], v[38:39], v[62:63], v[94:95] op_sel:[0,1,0] op_sel_hi:[1,1,1]
	v_pk_mul_f32 v[90:91], v[122:123], v[74:75] op_sel_hi:[1,0]
	v_add_f32_dpp v84, v84, v84 row_mirror row_mask:0xf bank_mask:0xf bound_ctrl:1
	v_pk_mul_f32 v[92:93], v[122:123], v[74:75] op_sel:[0,1] op_sel_hi:[1,1]
	v_add_f32_dpp v96, v95, v94 quad_perm:[1,0,3,2] row_mask:0xf bank_mask:0xf bound_ctrl:1
	ds_read_b128 v[60:63], v97 offset:12288
	v_mov_b32_dpp v85, v84 quad_perm:[1,0,3,2] row_mask:0xf bank_mask:0xf
	ds_write_b32 v99, v96 offset:6144
	v_pk_fma_f32 v[86:87], v[84:85], v[68:69], v[86:87] op_sel_hi:[1,0,1]
	v_pk_fma_f32 v[88:89], v[84:85], v[68:69], v[88:89] op_sel:[0,1,0] op_sel_hi:[1,1,1]
	v_pk_fma_f32 v[90:91], v[84:85], v[70:71], v[90:91] op_sel_hi:[1,0,1]
	v_pk_fma_f32 v[92:93], v[84:85], v[70:71], v[92:93] op_sel:[0,1,0] op_sel_hi:[1,1,1]
	v_pk_fma_f32 v[32:33], v[32:33], v[76:77], v[86:87] op_sel_hi:[1,0,1]
	v_pk_fma_f32 v[34:35], v[34:35], v[76:77], v[88:89] op_sel:[0,1,0] op_sel_hi:[1,1,1]
	v_pk_fma_f32 v[36:37], v[36:37], v[78:79], v[90:91] op_sel_hi:[1,0,1]
	v_pk_fma_f32 v[38:39], v[38:39], v[78:79], v[92:93] op_sel:[0,1,0] op_sel_hi:[1,1,1]
	ds_read_b128 v[64:67], v97 offset:14592
	s_waitcnt lgkmcnt(3)
; #define LAS __attribute__((address_space(3)))
; __device__ __forceinline__ float reduce8(float x) { x += dppf<0xB1>(x); x += dppf<0x4E>(x); x += dppf<0x141>(x); return x; }
; __device__ __forceinline__ void phase_scan(CParams& p, LAS unsigned char* lds) {
;     ...
;                 for (int g16 = 0; g16 < nst; g16 += 16) {
;                     unsigned ywb = (unsigned)(YP_OFF + (g16 >> 4) * YP_BYTES + (wid * 64 + lane) * 4);
;                     asm volatile("" : "+v"(ywb));
;                     LAS float* yw = (LAS float*)(lds + ywb);
; #pragma unroll
;                     for (int s16 = 0; s16 < 16; ++s16) {
;                         scan_ld(nxt, base + (g16 + s16 + 1) * 384, vb + (g16 + s16 + 1) * 384);
;                         f32x2 d = S[0] * cur.n0.lo; d = S[1] * cur.n0.hi + d; d = S[2] * cur.n1.lo + d; d = S[3] * cur.n1.hi + d;
;                         const float sa = reduce8(d.x + d.y);
;                         const f32x2 sa2 = (f32x2){sa, sa}, v2 = (f32x2){cur.v, cur.v};
;                         S[0] = S[0] * cur.w0.lo + (cur.b0.lo * sa2 + cur.k0.lo * v2);
;                         S[1] = S[1] * cur.w0.hi + (cur.b0.hi * sa2 + cur.k0.hi * v2);
;                         S[2] = S[2] * cur.w1.lo + (cur.b1.lo * sa2 + cur.k1.lo * v2);
;                         S[3] = S[3] * cur.w1.hi + (cur.b1.hi * sa2 + cur.k1.hi * v2);
;                         f32x2 e = S[0] * cur.r0.lo; e = S[1] * cur.r0.hi + e; e = S[2] * cur.r1.lo + e; e = S[3] * cur.r1.hi + e;
;                         yw[s16 * 256] = e.x + e.y;
;                         cur = nxt;
;                     }
	v_pk_mul_f32 v[84:85], v[32:33], v[40:41] op_sel_hi:[1,0]
	ds_read_b128 v[68:71], v97 offset:14848
	v_pk_fma_f32 v[84:85], v[34:35], v[40:41], v[84:85] op_sel:[0,1,0] op_sel_hi:[1,1,1]
	ds_read_b64 v[58:59], v98 offset:13824
	v_pk_fma_f32 v[84:85], v[36:37], v[42:43], v[84:85] op_sel_hi:[1,0,1]
	ds_read_b128 v[72:75], v97 offset:14336
	v_pk_fma_f32 v[84:85], v[38:39], v[42:43], v[84:85] op_sel:[0,1,0] op_sel_hi:[1,1,1]
	ds_read_b128 v[76:79], v97 offset:14080
	v_pk_mul_f32 v[94:95], v[32:33], v[80:81] op_sel_hi:[1,0]
	v_cndmask_b32_e32 v122, v56, v57, vcc
	v_cndmask_b32_e32 v123, v57, v56, vcc
	v_add_f32_dpp v84, v85, v84 quad_perm:[1,0,3,2] row_mask:0xf bank_mask:0xf bound_ctrl:1
	v_pk_fma_f32 v[94:95], v[34:35], v[80:81], v[94:95] op_sel:[0,1,0] op_sel_hi:[1,1,1]
	v_pk_mul_f32 v[86:87], v[122:123], v[48:49] op_sel_hi:[1,0]
	v_add_f32_dpp v84, v84, v84 quad_perm:[3,2,1,0] row_mask:0xf bank_mask:0xf bound_ctrl:1
	v_pk_fma_f32 v[94:95], v[36:37], v[82:83], v[94:95] op_sel_hi:[1,0,1]
	v_pk_mul_f32 v[88:89], v[122:123], v[48:49] op_sel:[0,1] op_sel_hi:[1,1]
	v_add_f32_dpp v84, v84, v84 row_half_mirror row_mask:0xf bank_mask:0xf bound_ctrl:1
	v_pk_fma_f32 v[94:95], v[38:39], v[82:83], v[94:95] op_sel:[0,1,0] op_sel_hi:[1,1,1]
	v_pk_mul_f32 v[90:91], v[122:123], v[50:51] op_sel_hi:[1,0]
	v_add_f32_dpp v84, v84, v84 row_mirror row_mask:0xf bank_mask:0xf bound_ctrl:1
	v_pk_mul_f32 v[92:93], v[122:123], v[50:51] op_sel:[0,1] op_sel_hi:[1,1]
	v_add_f32_dpp v96, v95, v94 quad_perm:[1,0,3,2] row_mask:0xf bank_mask:0xf bound_ctrl:1
	ds_read_b128 v[80:83], v97 offset:13824
	v_mov_b32_dpp v85, v84 quad_perm:[1,0,3,2] row_mask:0xf bank_mask:0xf
	ds_write_b32 v99, v96 offset:7168
	v_pk_fma_f32 v[86:87], v[84:85], v[44:45], v[86:87] op_sel_hi:[1,0,1]
	v_pk_fma_f32 v[88:89], v[84:85], v[44:45], v[88:89] op_sel:[0,1,0] op_sel_hi:[1,1,1]
	v_pk_fma_f32 v[90:91], v[84:85], v[46:47], v[90:91] op_sel_hi:[1,0,1]
	v_pk_fma_f32 v[92:93], v[84:85], v[46:47], v[92:93] op_sel:[0,1,0] op_sel_hi:[1,1,1]
	v_pk_fma_f32 v[32:33], v[32:33], v[52:53], v[86:87] op_sel_hi:[1,0,1]
	v_pk_fma_f32 v[34:35], v[34:35], v[52:53], v[88:89] op_sel:[0,1,0] op_sel_hi:[1,1,1]
	v_pk_fma_f32 v[36:37], v[36:37], v[54:55], v[90:91] op_sel_hi:[1,0,1]
	v_pk_fma_f32 v[38:39], v[38:39], v[54:55], v[92:93] op_sel:[0,1,0] op_sel_hi:[1,1,1]
	ds_read_b128 v[40:43], v97 offset:16128
	s_waitcnt lgkmcnt(3)
	v_pk_mul_f32 v[84:85], v[32:33], v[64:65] op_sel_hi:[1,0]
	ds_read_b128 v[44:47], v97 offset:16384
	v_pk_fma_f32 v[84:85], v[34:35], v[64:65], v[84:85] op_sel:[0,1,0] op_sel_hi:[1,1,1]
	ds_read_b64 v[56:57], v98 offset:15360
	v_pk_fma_f32 v[84:85], v[36:37], v[66:67], v[84:85] op_sel_hi:[1,0,1]
	ds_read_b128 v[48:51], v97 offset:15872
	v_pk_fma_f32 v[84:85], v[38:39], v[66:67], v[84:85] op_sel:[0,1,0] op_sel_hi:[1,1,1]
	ds_read_b128 v[52:55], v97 offset:15616
	v_pk_mul_f32 v[94:95], v[32:33], v[60:61] op_sel_hi:[1,0]
	v_cndmask_b32_e32 v122, v58, v59, vcc
	v_cndmask_b32_e32 v123, v59, v58, vcc
	v_add_f32_dpp v84, v85, v84 quad_perm:[1,0,3,2] row_mask:0xf bank_mask:0xf bound_ctrl:1
	v_pk_fma_f32 v[94:95], v[34:35], v[60:61], v[94:95] op_sel:[0,1,0] op_sel_hi:[1,1,1]
	v_pk_mul_f32 v[86:87], v[122:123], v[72:73] op_sel_hi:[1,0]
	v_add_f32_dpp v84, v84, v84 quad_perm:[3,2,1,0] row_mask:0xf bank_mask:0xf bound_ctrl:1
	v_pk_fma_f32 v[94:95], v[36:37], v[62:63], v[94:95] op_sel_hi:[1,0,1]
	v_pk_mul_f32 v[88:89], v[122:123], v[72:73] op_sel:[0,1] op_sel_hi:[1,1]
	v_add_f32_dpp v84, v84, v84 row_half_mirror row_mask:0xf bank_mask:0xf bound_ctrl:1
	v_pk_fma_f32 v[94:95], v[38:39], v[62:63], v[94:95] op_sel:[0,1,0] op_sel_hi:[1,1,1]
	v_pk_mul_f32 v[90:91], v[122:123], v[74:75] op_sel_hi:[1,0]
	v_add_f32_dpp v84, v84, v84 row_mirror row_mask:0xf bank_mask:0xf bound_ctrl:1
	v_pk_mul_f32 v[92:93], v[122:123], v[74:75] op_sel:[0,1] op_sel_hi:[1,1]
	v_add_f32_dpp v96, v95, v94 quad_perm:[1,0,3,2] row_mask:0xf bank_mask:0xf bound_ctrl:1
	ds_read_b128 v[60:63], v97 offset:15360
	v_mov_b32_dpp v85, v84 quad_perm:[1,0,3,2] row_mask:0xf bank_mask:0xf
	ds_write_b32 v99, v96 offset:8192
	v_pk_fma_f32 v[86:87], v[84:85], v[68:69], v[86:87] op_sel_hi:[1,0,1]
	v_pk_fma_f32 v[88:89], v[84:85], v[68:69], v[88:89] op_sel:[0,1,0] op_sel_hi:[1,1,1]
	v_pk_fma_f32 v[90:91], v[84:85], v[70:71], v[90:91] op_sel_hi:[1,0,1]
	v_pk_fma_f32 v[92:93], v[84:85], v[70:71], v[92:93] op_sel:[0,1,0] op_sel_hi:[1,1,1]
	v_pk_fma_f32 v[32:33], v[32:33], v[76:77], v[86:87] op_sel_hi:[1,0,1]
	v_pk_fma_f32 v[34:35], v[34:35], v[76:77], v[88:89] op_sel:[0,1,0] op_sel_hi:[1,1,1]
	v_pk_fma_f32 v[36:37], v[36:37], v[78:79], v[90:91] op_sel_hi:[1,0,1]
	v_pk_fma_f32 v[38:39], v[38:39], v[78:79], v[92:93] op_sel:[0,1,0] op_sel_hi:[1,1,1]
	ds_read_b128 v[64:67], v97 offset:17664
	s_waitcnt lgkmcnt(3)
; #define LAS __attribute__((address_space(3)))
; __device__ __forceinline__ float reduce8(float x) { x += dppf<0xB1>(x); x += dppf<0x4E>(x); x += dppf<0x141>(x); return x; }
; __device__ __forceinline__ void phase_scan(CParams& p, LAS unsigned char* lds) {
;     ...
;                 for (int g16 = 0; g16 < nst; g16 += 16) {
;                     unsigned ywb = (unsigned)(YP_OFF + (g16 >> 4) * YP_BYTES + (wid * 64 + lane) * 4);
;                     asm volatile("" : "+v"(ywb));
;                     LAS float* yw = (LAS float*)(lds + ywb);
; #pragma unroll
;                     for (int s16 = 0; s16 < 16; ++s16) {
;                         scan_ld(nxt, base + (g16 + s16 + 1) * 384, vb + (g16 + s16 + 1) * 384);
;                         f32x2 d = S[0] * cur.n0.lo; d = S[1] * cur.n0.hi + d; d = S[2] * cur.n1.lo + d; d = S[3] * cur.n1.hi + d;
;                         const float sa = reduce8(d.x + d.y);
;                         const f32x2 sa2 = (f32x2){sa, sa}, v2 = (f32x2){cur.v, cur.v};
;                         S[0] = S[0] * cur.w0.lo + (cur.b0.lo * sa2 + cur.k0.lo * v2);
;                         S[1] = S[1] * cur.w0.hi + (cur.b0.hi * sa2 + cur.k0.hi * v2);
;                         S[2] = S[2] * cur.w1.lo + (cur.b1.lo * sa2 + cur.k1.lo * v2);
;                         S[3] = S[3] * cur.w1.hi + (cur.b1.hi * sa2 + cur.k1.hi * v2);
;                         f32x2 e = S[0] * cur.r0.lo; e = S[1] * cur.r0.hi + e; e = S[2] * cur.r1.lo + e; e = S[3] * cur.r1.hi + e;
;                         yw[s16 * 256] = e.x + e.y;
;                         cur = nxt;
;                     }
	v_pk_mul_f32 v[84:85], v[32:33], v[40:41] op_sel_hi:[1,0]
	ds_read_b128 v[68:71], v97 offset:17920
	v_pk_fma_f32 v[84:85], v[34:35], v[40:41], v[84:85] op_sel:[0,1,0] op_sel_hi:[1,1,1]
	ds_read_b64 v[58:59], v98 offset:16896
	v_pk_fma_f32 v[84:85], v[36:37], v[42:43], v[84:85] op_sel_hi:[1,0,1]
	ds_read_b128 v[72:75], v97 offset:17408
	v_pk_fma_f32 v[84:85], v[38:39], v[42:43], v[84:85] op_sel:[0,1,0] op_sel_hi:[1,1,1]
	ds_read_b128 v[76:79], v97 offset:17152
	v_pk_mul_f32 v[94:95], v[32:33], v[80:81] op_sel_hi:[1,0]
	v_cndmask_b32_e32 v122, v56, v57, vcc
	v_cndmask_b32_e32 v123, v57, v56, vcc
	v_add_f32_dpp v84, v85, v84 quad_perm:[1,0,3,2] row_mask:0xf bank_mask:0xf bound_ctrl:1
	v_pk_fma_f32 v[94:95], v[34:35], v[80:81], v[94:95] op_sel:[0,1,0] op_sel_hi:[1,1,1]
	v_pk_mul_f32 v[86:87], v[122:123], v[48:49] op_sel_hi:[1,0]
	v_add_f32_dpp v84, v84, v84 quad_perm:[3,2,1,0] row_mask:0xf bank_mask:0xf bound_ctrl:1
	v_pk_fma_f32 v[94:95], v[36:37], v[82:83], v[94:95] op_sel_hi:[1,0,1]
	v_pk_mul_f32 v[88:89], v[122:123], v[48:49] op_sel:[0,1] op_sel_hi:[1,1]
	v_add_f32_dpp v84, v84, v84 row_half_mirror row_mask:0xf bank_mask:0xf bound_ctrl:1
	v_pk_fma_f32 v[94:95], v[38:39], v[82:83], v[94:95] op_sel:[0,1,0] op_sel_hi:[1,1,1]
	v_pk_mul_f32 v[90:91], v[122:123], v[50:51] op_sel_hi:[1,0]
	v_add_f32_dpp v84, v84, v84 row_mirror row_mask:0xf bank_mask:0xf bound_ctrl:1
	v_pk_mul_f32 v[92:93], v[122:123], v[50:51] op_sel:[0,1] op_sel_hi:[1,1]
	v_add_f32_dpp v96, v95, v94 quad_perm:[1,0,3,2] row_mask:0xf bank_mask:0xf bound_ctrl:1
	ds_read_b128 v[80:83], v97 offset:16896
	v_mov_b32_dpp v85, v84 quad_perm:[1,0,3,2] row_mask:0xf bank_mask:0xf
	ds_write_b32 v99, v96 offset:9216
	v_pk_fma_f32 v[86:87], v[84:85], v[44:45], v[86:87] op_sel_hi:[1,0,1]
	v_pk_fma_f32 v[88:89], v[84:85], v[44:45], v[88:89] op_sel:[0,1,0] op_sel_hi:[1,1,1]
	v_pk_fma_f32 v[90:91], v[84:85], v[46:47], v[90:91] op_sel_hi:[1,0,1]
	v_pk_fma_f32 v[92:93], v[84:85], v[46:47], v[92:93] op_sel:[0,1,0] op_sel_hi:[1,1,1]
	v_pk_fma_f32 v[32:33], v[32:33], v[52:53], v[86:87] op_sel_hi:[1,0,1]
	v_pk_fma_f32 v[34:35], v[34:35], v[52:53], v[88:89] op_sel:[0,1,0] op_sel_hi:[1,1,1]
	v_pk_fma_f32 v[36:37], v[36:37], v[54:55], v[90:91] op_sel_hi:[1,0,1]
	v_pk_fma_f32 v[38:39], v[38:39], v[54:55], v[92:93] op_sel:[0,1,0] op_sel_hi:[1,1,1]
	ds_read_b128 v[40:43], v97 offset:19200
	s_waitcnt lgkmcnt(3)
	v_pk_mul_f32 v[84:85], v[32:33], v[64:65] op_sel_hi:[1,0]
	ds_read_b128 v[44:47], v97 offset:19456
	v_pk_fma_f32 v[84:85], v[34:35], v[64:65], v[84:85] op_sel:[0,1,0] op_sel_hi:[1,1,1]
	ds_read_b64 v[56:57], v98 offset:18432
	v_pk_fma_f32 v[84:85], v[36:37], v[66:67], v[84:85] op_sel_hi:[1,0,1]
	ds_read_b128 v[48:51], v97 offset:18944
	v_pk_fma_f32 v[84:85], v[38:39], v[66:67], v[84:85] op_sel:[0,1,0] op_sel_hi:[1,1,1]
	ds_read_b128 v[52:55], v97 offset:18688
	v_pk_mul_f32 v[94:95], v[32:33], v[60:61] op_sel_hi:[1,0]
	v_cndmask_b32_e32 v122, v58, v59, vcc
	v_cndmask_b32_e32 v123, v59, v58, vcc
	v_add_f32_dpp v84, v85, v84 quad_perm:[1,0,3,2] row_mask:0xf bank_mask:0xf bound_ctrl:1
	v_pk_fma_f32 v[94:95], v[34:35], v[60:61], v[94:95] op_sel:[0,1,0] op_sel_hi:[1,1,1]
	v_pk_mul_f32 v[86:87], v[122:123], v[72:73] op_sel_hi:[1,0]
	v_add_f32_dpp v84, v84, v84 quad_perm:[3,2,1,0] row_mask:0xf bank_mask:0xf bound_ctrl:1
	v_pk_fma_f32 v[94:95], v[36:37], v[62:63], v[94:95] op_sel_hi:[1,0,1]
	v_pk_mul_f32 v[88:89], v[122:123], v[72:73] op_sel:[0,1] op_sel_hi:[1,1]
	v_add_f32_dpp v84, v84, v84 row_half_mirror row_mask:0xf bank_mask:0xf bound_ctrl:1
	v_pk_fma_f32 v[94:95], v[38:39], v[62:63], v[94:95] op_sel:[0,1,0] op_sel_hi:[1,1,1]
	v_pk_mul_f32 v[90:91], v[122:123], v[74:75] op_sel_hi:[1,0]
	v_add_f32_dpp v84, v84, v84 row_mirror row_mask:0xf bank_mask:0xf bound_ctrl:1
	v_pk_mul_f32 v[92:93], v[122:123], v[74:75] op_sel:[0,1] op_sel_hi:[1,1]
	v_add_f32_dpp v96, v95, v94 quad_perm:[1,0,3,2] row_mask:0xf bank_mask:0xf bound_ctrl:1
	ds_read_b128 v[60:63], v97 offset:18432
	v_mov_b32_dpp v85, v84 quad_perm:[1,0,3,2] row_mask:0xf bank_mask:0xf
	ds_write_b32 v99, v96 offset:10240
	v_pk_fma_f32 v[86:87], v[84:85], v[68:69], v[86:87] op_sel_hi:[1,0,1]
	v_pk_fma_f32 v[88:89], v[84:85], v[68:69], v[88:89] op_sel:[0,1,0] op_sel_hi:[1,1,1]
	v_pk_fma_f32 v[90:91], v[84:85], v[70:71], v[90:91] op_sel_hi:[1,0,1]
	v_pk_fma_f32 v[92:93], v[84:85], v[70:71], v[92:93] op_sel:[0,1,0] op_sel_hi:[1,1,1]
	v_pk_fma_f32 v[32:33], v[32:33], v[76:77], v[86:87] op_sel_hi:[1,0,1]
	v_pk_fma_f32 v[34:35], v[34:35], v[76:77], v[88:89] op_sel:[0,1,0] op_sel_hi:[1,1,1]
	v_pk_fma_f32 v[36:37], v[36:37], v[78:79], v[90:91] op_sel_hi:[1,0,1]
	v_pk_fma_f32 v[38:39], v[38:39], v[78:79], v[92:93] op_sel:[0,1,0] op_sel_hi:[1,1,1]
	ds_read_b128 v[64:67], v97 offset:20736
	s_waitcnt lgkmcnt(3)
; #define LAS __attribute__((address_space(3)))
; __device__ __forceinline__ float reduce8(float x) { x += dppf<0xB1>(x); x += dppf<0x4E>(x); x += dppf<0x141>(x); return x; }
; __device__ __forceinline__ void phase_scan(CParams& p, LAS unsigned char* lds) {
;     ...
;                 for (int g16 = 0; g16 < nst; g16 += 16) {
;                     unsigned ywb = (unsigned)(YP_OFF + (g16 >> 4) * YP_BYTES + (wid * 64 + lane) * 4);
;                     asm volatile("" : "+v"(ywb));
;                     LAS float* yw = (LAS float*)(lds + ywb);
; #pragma unroll
;                     for (int s16 = 0; s16 < 16; ++s16) {
;                         scan_ld(nxt, base + (g16 + s16 + 1) * 384, vb + (g16 + s16 + 1) * 384);
;                         f32x2 d = S[0] * cur.n0.lo; d = S[1] * cur.n0.hi + d; d = S[2] * cur.n1.lo + d; d = S[3] * cur.n1.hi + d;
;                         const float sa = reduce8(d.x + d.y);
;                         const f32x2 sa2 = (f32x2){sa, sa}, v2 = (f32x2){cur.v, cur.v};
;                         S[0] = S[0] * cur.w0.lo + (cur.b0.lo * sa2 + cur.k0.lo * v2);
;                         S[1] = S[1] * cur.w0.hi + (cur.b0.hi * sa2 + cur.k0.hi * v2);
;                         S[2] = S[2] * cur.w1.lo + (cur.b1.lo * sa2 + cur.k1.lo * v2);
;                         S[3] = S[3] * cur.w1.hi + (cur.b1.hi * sa2 + cur.k1.hi * v2);
;                         f32x2 e = S[0] * cur.r0.lo; e = S[1] * cur.r0.hi + e; e = S[2] * cur.r1.lo + e; e = S[3] * cur.r1.hi + e;
;                         yw[s16 * 256] = e.x + e.y;
;                         cur = nxt;
;                     }
	v_pk_mul_f32 v[84:85], v[32:33], v[40:41] op_sel_hi:[1,0]
	ds_read_b128 v[68:71], v97 offset:20992
	v_pk_fma_f32 v[84:85], v[34:35], v[40:41], v[84:85] op_sel:[0,1,0] op_sel_hi:[1,1,1]
	ds_read_b64 v[58:59], v98 offset:19968
	v_pk_fma_f32 v[84:85], v[36:37], v[42:43], v[84:85] op_sel_hi:[1,0,1]
	ds_read_b128 v[72:75], v97 offset:20480
	v_pk_fma_f32 v[84:85], v[38:39], v[42:43], v[84:85] op_sel:[0,1,0] op_sel_hi:[1,1,1]
	ds_read_b128 v[76:79], v97 offset:20224
	v_pk_mul_f32 v[94:95], v[32:33], v[80:81] op_sel_hi:[1,0]
	v_cndmask_b32_e32 v122, v56, v57, vcc
	v_cndmask_b32_e32 v123, v57, v56, vcc
	v_add_f32_dpp v84, v85, v84 quad_perm:[1,0,3,2] row_mask:0xf bank_mask:0xf bound_ctrl:1
	v_pk_fma_f32 v[94:95], v[34:35], v[80:81], v[94:95] op_sel:[0,1,0] op_sel_hi:[1,1,1]
	v_pk_mul_f32 v[86:87], v[122:123], v[48:49] op_sel_hi:[1,0]
	v_add_f32_dpp v84, v84, v84 quad_perm:[3,2,1,0] row_mask:0xf bank_mask:0xf bound_ctrl:1
	v_pk_fma_f32 v[94:95], v[36:37], v[82:83], v[94:95] op_sel_hi:[1,0,1]
	v_pk_mul_f32 v[88:89], v[122:123], v[48:49] op_sel:[0,1] op_sel_hi:[1,1]
	v_add_f32_dpp v84, v84, v84 row_half_mirror row_mask:0xf bank_mask:0xf bound_ctrl:1
	v_pk_fma_f32 v[94:95], v[38:39], v[82:83], v[94:95] op_sel:[0,1,0] op_sel_hi:[1,1,1]
	v_pk_mul_f32 v[90:91], v[122:123], v[50:51] op_sel_hi:[1,0]
	v_add_f32_dpp v84, v84, v84 row_mirror row_mask:0xf bank_mask:0xf bound_ctrl:1
	v_pk_mul_f32 v[92:93], v[122:123], v[50:51] op_sel:[0,1] op_sel_hi:[1,1]
	v_add_f32_dpp v96, v95, v94 quad_perm:[1,0,3,2] row_mask:0xf bank_mask:0xf bound_ctrl:1
	ds_read_b128 v[80:83], v97 offset:19968
	v_mov_b32_dpp v85, v84 quad_perm:[1,0,3,2] row_mask:0xf bank_mask:0xf
	ds_write_b32 v99, v96 offset:11264
	v_pk_fma_f32 v[86:87], v[84:85], v[44:45], v[86:87] op_sel_hi:[1,0,1]
	v_pk_fma_f32 v[88:89], v[84:85], v[44:45], v[88:89] op_sel:[0,1,0] op_sel_hi:[1,1,1]
	v_pk_fma_f32 v[90:91], v[84:85], v[46:47], v[90:91] op_sel_hi:[1,0,1]
	v_pk_fma_f32 v[92:93], v[84:85], v[46:47], v[92:93] op_sel:[0,1,0] op_sel_hi:[1,1,1]
	v_pk_fma_f32 v[32:33], v[32:33], v[52:53], v[86:87] op_sel_hi:[1,0,1]
	v_pk_fma_f32 v[34:35], v[34:35], v[52:53], v[88:89] op_sel:[0,1,0] op_sel_hi:[1,1,1]
	v_pk_fma_f32 v[36:37], v[36:37], v[54:55], v[90:91] op_sel_hi:[1,0,1]
	v_pk_fma_f32 v[38:39], v[38:39], v[54:55], v[92:93] op_sel:[0,1,0] op_sel_hi:[1,1,1]
	ds_read_b128 v[40:43], v97 offset:22272
	s_waitcnt lgkmcnt(3)
	v_pk_mul_f32 v[84:85], v[32:33], v[64:65] op_sel_hi:[1,0]
	ds_read_b128 v[44:47], v97 offset:22528
	v_pk_fma_f32 v[84:85], v[34:35], v[64:65], v[84:85] op_sel:[0,1,0] op_sel_hi:[1,1,1]
	ds_read_b64 v[56:57], v98 offset:21504
	v_pk_fma_f32 v[84:85], v[36:37], v[66:67], v[84:85] op_sel_hi:[1,0,1]
	ds_read_b128 v[48:51], v97 offset:22016
	v_pk_fma_f32 v[84:85], v[38:39], v[66:67], v[84:85] op_sel:[0,1,0] op_sel_hi:[1,1,1]
	ds_read_b128 v[52:55], v97 offset:21760
	v_pk_mul_f32 v[94:95], v[32:33], v[60:61] op_sel_hi:[1,0]
	v_cndmask_b32_e32 v122, v58, v59, vcc
	v_cndmask_b32_e32 v123, v59, v58, vcc
	v_add_f32_dpp v84, v85, v84 quad_perm:[1,0,3,2] row_mask:0xf bank_mask:0xf bound_ctrl:1
	v_pk_fma_f32 v[94:95], v[34:35], v[60:61], v[94:95] op_sel:[0,1,0] op_sel_hi:[1,1,1]
	v_pk_mul_f32 v[86:87], v[122:123], v[72:73] op_sel_hi:[1,0]
	v_add_f32_dpp v84, v84, v84 quad_perm:[3,2,1,0] row_mask:0xf bank_mask:0xf bound_ctrl:1
	v_pk_fma_f32 v[94:95], v[36:37], v[62:63], v[94:95] op_sel_hi:[1,0,1]
	v_pk_mul_f32 v[88:89], v[122:123], v[72:73] op_sel:[0,1] op_sel_hi:[1,1]
	v_add_f32_dpp v84, v84, v84 row_half_mirror row_mask:0xf bank_mask:0xf bound_ctrl:1
	v_pk_fma_f32 v[94:95], v[38:39], v[62:63], v[94:95] op_sel:[0,1,0] op_sel_hi:[1,1,1]
	v_pk_mul_f32 v[90:91], v[122:123], v[74:75] op_sel_hi:[1,0]
	v_add_f32_dpp v84, v84, v84 row_mirror row_mask:0xf bank_mask:0xf bound_ctrl:1
	v_pk_mul_f32 v[92:93], v[122:123], v[74:75] op_sel:[0,1] op_sel_hi:[1,1]
	v_add_f32_dpp v96, v95, v94 quad_perm:[1,0,3,2] row_mask:0xf bank_mask:0xf bound_ctrl:1
	ds_read_b128 v[60:63], v97 offset:21504
	v_mov_b32_dpp v85, v84 quad_perm:[1,0,3,2] row_mask:0xf bank_mask:0xf
	ds_write_b32 v99, v96 offset:12288
	v_pk_fma_f32 v[86:87], v[84:85], v[68:69], v[86:87] op_sel_hi:[1,0,1]
	v_pk_fma_f32 v[88:89], v[84:85], v[68:69], v[88:89] op_sel:[0,1,0] op_sel_hi:[1,1,1]
	v_pk_fma_f32 v[90:91], v[84:85], v[70:71], v[90:91] op_sel_hi:[1,0,1]
	v_pk_fma_f32 v[92:93], v[84:85], v[70:71], v[92:93] op_sel:[0,1,0] op_sel_hi:[1,1,1]
	v_pk_fma_f32 v[32:33], v[32:33], v[76:77], v[86:87] op_sel_hi:[1,0,1]
	v_pk_fma_f32 v[34:35], v[34:35], v[76:77], v[88:89] op_sel:[0,1,0] op_sel_hi:[1,1,1]
	v_pk_fma_f32 v[36:37], v[36:37], v[78:79], v[90:91] op_sel_hi:[1,0,1]
	v_pk_fma_f32 v[38:39], v[38:39], v[78:79], v[92:93] op_sel:[0,1,0] op_sel_hi:[1,1,1]
	ds_read_b128 v[64:67], v97 offset:23808
	s_waitcnt lgkmcnt(3)
; #define LAS __attribute__((address_space(3)))
; __device__ __forceinline__ float reduce8(float x) { x += dppf<0xB1>(x); x += dppf<0x4E>(x); x += dppf<0x141>(x); return x; }
; __device__ __forceinline__ void phase_scan(CParams& p, LAS unsigned char* lds) {
;     ...
;                 for (int g16 = 0; g16 < nst; g16 += 16) {
;                     unsigned ywb = (unsigned)(YP_OFF + (g16 >> 4) * YP_BYTES + (wid * 64 + lane) * 4);
;                     asm volatile("" : "+v"(ywb));
;                     LAS float* yw = (LAS float*)(lds + ywb);
; #pragma unroll
;                     for (int s16 = 0; s16 < 16; ++s16) {
;                         scan_ld(nxt, base + (g16 + s16 + 1) * 384, vb + (g16 + s16 + 1) * 384);
;                         f32x2 d = S[0] * cur.n0.lo; d = S[1] * cur.n0.hi + d; d = S[2] * cur.n1.lo + d; d = S[3] * cur.n1.hi + d;
;                         const float sa = reduce8(d.x + d.y);
;                         const f32x2 sa2 = (f32x2){sa, sa}, v2 = (f32x2){cur.v, cur.v};
;                         S[0] = S[0] * cur.w0.lo + (cur.b0.lo * sa2 + cur.k0.lo * v2);
;                         S[1] = S[1] * cur.w0.hi + (cur.b0.hi * sa2 + cur.k0.hi * v2);
;                         S[2] = S[2] * cur.w1.lo + (cur.b1.lo * sa2 + cur.k1.lo * v2);
;                         S[3] = S[3] * cur.w1.hi + (cur.b1.hi * sa2 + cur.k1.hi * v2);
;                         f32x2 e = S[0] * cur.r0.lo; e = S[1] * cur.r0.hi + e; e = S[2] * cur.r1.lo + e; e = S[3] * cur.r1.hi + e;
;                         yw[s16 * 256] = e.x + e.y;
;                         cur = nxt;
;                     }
;                     __syncthreads();
;                 }
;             }
;             float* so = p.out + (prompt ? O_WP : O_WS) + ((size_t)chain * 64 + row) * 64;
;             *(f32x4*)(so + 4 * j) = (f32x4){S[0].x, S[0].y, S[1].x, S[1].y}; *(f32x4*)(so + 32 + 4 * j) = (f32x4){S[2].x, S[2].y, S[3].x, S[3].y};
;             __syncthreads();
	v_pk_mul_f32 v[84:85], v[32:33], v[40:41] op_sel_hi:[1,0]
	ds_read_b128 v[68:71], v97 offset:24064
	v_pk_fma_f32 v[84:85], v[34:35], v[40:41], v[84:85] op_sel:[0,1,0] op_sel_hi:[1,1,1]
	ds_read_b64 v[58:59], v98 offset:23040
	v_pk_fma_f32 v[84:85], v[36:37], v[42:43], v[84:85] op_sel_hi:[1,0,1]
	ds_read_b128 v[72:75], v97 offset:23552
	v_pk_fma_f32 v[84:85], v[38:39], v[42:43], v[84:85] op_sel:[0,1,0] op_sel_hi:[1,1,1]
	ds_read_b128 v[76:79], v97 offset:23296
	v_pk_mul_f32 v[94:95], v[32:33], v[80:81] op_sel_hi:[1,0]
	v_cndmask_b32_e32 v122, v56, v57, vcc
	v_cndmask_b32_e32 v123, v57, v56, vcc
	v_add_f32_dpp v84, v85, v84 quad_perm:[1,0,3,2] row_mask:0xf bank_mask:0xf bound_ctrl:1
	v_pk_fma_f32 v[94:95], v[34:35], v[80:81], v[94:95] op_sel:[0,1,0] op_sel_hi:[1,1,1]
	v_pk_mul_f32 v[86:87], v[122:123], v[48:49] op_sel_hi:[1,0]
	v_add_f32_dpp v84, v84, v84 quad_perm:[3,2,1,0] row_mask:0xf bank_mask:0xf bound_ctrl:1
	v_pk_fma_f32 v[94:95], v[36:37], v[82:83], v[94:95] op_sel_hi:[1,0,1]
	v_pk_mul_f32 v[88:89], v[122:123], v[48:49] op_sel:[0,1] op_sel_hi:[1,1]
	v_add_f32_dpp v84, v84, v84 row_half_mirror row_mask:0xf bank_mask:0xf bound_ctrl:1
	v_pk_fma_f32 v[94:95], v[38:39], v[82:83], v[94:95] op_sel:[0,1,0] op_sel_hi:[1,1,1]
	v_pk_mul_f32 v[90:91], v[122:123], v[50:51] op_sel_hi:[1,0]
	v_add_f32_dpp v84, v84, v84 row_mirror row_mask:0xf bank_mask:0xf bound_ctrl:1
	v_pk_mul_f32 v[92:93], v[122:123], v[50:51] op_sel:[0,1] op_sel_hi:[1,1]
	v_add_f32_dpp v96, v95, v94 quad_perm:[1,0,3,2] row_mask:0xf bank_mask:0xf bound_ctrl:1
	ds_read_b128 v[80:83], v97 offset:23040
	v_mov_b32_dpp v85, v84 quad_perm:[1,0,3,2] row_mask:0xf bank_mask:0xf
	ds_write_b32 v99, v96 offset:13312
	v_pk_fma_f32 v[86:87], v[84:85], v[44:45], v[86:87] op_sel_hi:[1,0,1]
	v_pk_fma_f32 v[88:89], v[84:85], v[44:45], v[88:89] op_sel:[0,1,0] op_sel_hi:[1,1,1]
	v_pk_fma_f32 v[90:91], v[84:85], v[46:47], v[90:91] op_sel_hi:[1,0,1]
	v_pk_fma_f32 v[92:93], v[84:85], v[46:47], v[92:93] op_sel:[0,1,0] op_sel_hi:[1,1,1]
	v_pk_fma_f32 v[32:33], v[32:33], v[52:53], v[86:87] op_sel_hi:[1,0,1]
	v_pk_fma_f32 v[34:35], v[34:35], v[52:53], v[88:89] op_sel:[0,1,0] op_sel_hi:[1,1,1]
	v_pk_fma_f32 v[36:37], v[36:37], v[54:55], v[90:91] op_sel_hi:[1,0,1]
	v_pk_fma_f32 v[38:39], v[38:39], v[54:55], v[92:93] op_sel:[0,1,0] op_sel_hi:[1,1,1]
	ds_read_b128 v[40:43], v97 offset:25344
	s_waitcnt lgkmcnt(3)
	v_pk_mul_f32 v[84:85], v[32:33], v[64:65] op_sel_hi:[1,0]
	ds_read_b128 v[44:47], v97 offset:25600
	v_pk_fma_f32 v[84:85], v[34:35], v[64:65], v[84:85] op_sel:[0,1,0] op_sel_hi:[1,1,1]
	ds_read_b64 v[56:57], v98 offset:24576
	v_pk_fma_f32 v[84:85], v[36:37], v[66:67], v[84:85] op_sel_hi:[1,0,1]
	ds_read_b128 v[48:51], v97 offset:25088
	v_pk_fma_f32 v[84:85], v[38:39], v[66:67], v[84:85] op_sel:[0,1,0] op_sel_hi:[1,1,1]
	ds_read_b128 v[52:55], v97 offset:24832
	v_pk_mul_f32 v[94:95], v[32:33], v[60:61] op_sel_hi:[1,0]
	v_cndmask_b32_e32 v122, v58, v59, vcc
	v_cndmask_b32_e32 v123, v59, v58, vcc
	v_add_f32_dpp v84, v85, v84 quad_perm:[1,0,3,2] row_mask:0xf bank_mask:0xf bound_ctrl:1
	v_pk_fma_f32 v[94:95], v[34:35], v[60:61], v[94:95] op_sel:[0,1,0] op_sel_hi:[1,1,1]
	v_pk_mul_f32 v[86:87], v[122:123], v[72:73] op_sel_hi:[1,0]
	v_add_f32_dpp v84, v84, v84 quad_perm:[3,2,1,0] row_mask:0xf bank_mask:0xf bound_ctrl:1
	v_pk_fma_f32 v[94:95], v[36:37], v[62:63], v[94:95] op_sel_hi:[1,0,1]
	v_pk_mul_f32 v[88:89], v[122:123], v[72:73] op_sel:[0,1] op_sel_hi:[1,1]
	v_add_f32_dpp v84, v84, v84 row_half_mirror row_mask:0xf bank_mask:0xf bound_ctrl:1
	v_pk_fma_f32 v[94:95], v[38:39], v[62:63], v[94:95] op_sel:[0,1,0] op_sel_hi:[1,1,1]
	v_pk_mul_f32 v[90:91], v[122:123], v[74:75] op_sel_hi:[1,0]
	v_add_f32_dpp v84, v84, v84 row_mirror row_mask:0xf bank_mask:0xf bound_ctrl:1
	v_pk_mul_f32 v[92:93], v[122:123], v[74:75] op_sel:[0,1] op_sel_hi:[1,1]
	v_add_f32_dpp v96, v95, v94 quad_perm:[1,0,3,2] row_mask:0xf bank_mask:0xf bound_ctrl:1
	ds_read_b128 v[60:63], v97 offset:24576
	v_mov_b32_dpp v85, v84 quad_perm:[1,0,3,2] row_mask:0xf bank_mask:0xf
	ds_write_b32 v99, v96 offset:14336
	v_pk_fma_f32 v[86:87], v[84:85], v[68:69], v[86:87] op_sel_hi:[1,0,1]
	v_pk_fma_f32 v[88:89], v[84:85], v[68:69], v[88:89] op_sel:[0,1,0] op_sel_hi:[1,1,1]
	v_pk_fma_f32 v[90:91], v[84:85], v[70:71], v[90:91] op_sel_hi:[1,0,1]
	v_pk_fma_f32 v[92:93], v[84:85], v[70:71], v[92:93] op_sel:[0,1,0] op_sel_hi:[1,1,1]
	v_pk_fma_f32 v[32:33], v[32:33], v[76:77], v[86:87] op_sel_hi:[1,0,1]
	v_pk_fma_f32 v[34:35], v[34:35], v[76:77], v[88:89] op_sel:[0,1,0] op_sel_hi:[1,1,1]
	v_pk_fma_f32 v[36:37], v[36:37], v[78:79], v[90:91] op_sel_hi:[1,0,1]
	v_pk_fma_f32 v[38:39], v[38:39], v[78:79], v[92:93] op_sel:[0,1,0] op_sel_hi:[1,1,1]
	s_waitcnt lgkmcnt(8)
	v_pk_mul_f32 v[94:95], v[32:33], v[80:81] op_sel_hi:[1,0]
	s_nop 0
	v_pk_fma_f32 v[94:95], v[34:35], v[80:81], v[94:95] op_sel:[0,1,0] op_sel_hi:[1,1,1]
	s_nop 0
	v_pk_fma_f32 v[94:95], v[36:37], v[82:83], v[94:95] op_sel_hi:[1,0,1]
	s_nop 0
	v_pk_fma_f32 v[94:95], v[38:39], v[82:83], v[94:95] op_sel:[0,1,0] op_sel_hi:[1,1,1]
	s_nop 1
	v_add_f32_dpp v96, v95, v94 quad_perm:[1,0,3,2] row_mask:0xf bank_mask:0xf bound_ctrl:1
	ds_write_b32 v99, v96 offset:15360
	s_add_i32 s15, s15, 16
	v_add_u32_e32 v97, 0x6000, v97
	v_add_u32_e32 v98, 0x6000, v98
	v_add_u32_e32 v99, 0x4000, v99
	s_waitcnt lgkmcnt(0)
	s_barrier
	s_cmp_lt_i32 s15, s54
	s_cbranch_scc1 .Lsc_grp
	s_add_i32 s13, s13, 1
	s_cmp_lt_u32 s13, s3
	s_cbranch_scc1 .Lsc_chunk
	s_mov_b32 s13, 0
	s_lshl_b64 s[54:55], s[12:13], 14
	s_cmp_eq_u64 s[50:51], 0
	s_mov_b32 s15, 0x94b6000
	s_cselect_b32 s15, 0x9192000, s15
	s_add_u32 s54, s54, s15
	s_addc_u32 s55, s55, 0
	s_add_u32 s54, s54, s40
	s_addc_u32 s55, s55, s41
	v_cndmask_b32_e32 v104, v32, v33, vcc
	v_cndmask_b32_e32 v108, v33, v32, vcc
	v_cndmask_b32_e32 v105, v34, v35, vcc
	v_cndmask_b32_e32 v109, v35, v34, vcc
	v_cndmask_b32_e32 v106, v36, v37, vcc
	v_cndmask_b32_e32 v110, v37, v36, vcc
	v_cndmask_b32_e32 v107, v38, v39, vcc
	v_cndmask_b32_e32 v111, v39, v38, vcc
	s_nop 1
	global_store_dwordx4 v103, v[104:107], s[54:55]
	global_store_dwordx4 v103, v[108:111], s[54:55] offset:256
	s_mov_b64 s[54:55], 0
	s_barrier
